# hyena: conditional neighbour loads issued together, one wait instead of 8 serialized vmcnt(0) per series
# speedup vs baseline: 1.0114x; 1.0114x over previous
.LBB0_505:
	s_add_i32 s10, s33, 0xfffffc00
	s_cmpk_lt_i32 s33, 0x400
	s_cselect_b64 s[8:9], -1, 0
	s_and_b64 s[8:9], s[8:9], exec
	s_cselect_b32 s10, s33, s10
	s_lshl_b32 s8, s10, 4
	s_and_b32 s11, s8, 0xfffff800
	s_add_i32 s12, s11, 0x2000
	s_cmpk_lt_i32 s33, 0x400
	s_cselect_b64 s[40:41], -1, 0
	v_mov_b32_e32 v123, v234
	s_and_b64 s[8:9], s[40:41], exec
	s_cselect_b32 s73, s47, 0x100
	v_readfirstlane_b32 s13, v123
	s_cselect_b32 s48, s12, s11
	s_lshl_b32 s8, s10, 3
	s_ashr_i32 s83, s13, 6
	s_and_b32 s79, s8, 0x3f8
	s_add_i32 s66, s83, s79
	s_add_i32 s8, s66, 0x800
	s_ashr_i32 s9, s8, 31
	s_lshl_b64 s[10:11], s[8:9], 2
	s_add_u32 s12, s52, s10
	s_addc_u32 s13, s53, s11
	s_ashr_i32 s67, s66, 31
	s_lshl_b64 s[14:15], s[66:67], 2
	s_add_u32 s68, s52, s14
	s_addc_u32 s69, s53, s15
	s_add_u32 s10, s54, s10
	s_addc_u32 s11, s55, s11
	s_mul_hi_i32 s9, s8, 0xc000
	s_mul_i32 s8, s8, 0xc000
	s_add_u32 s8, s60, s8
	s_addc_u32 s9, s61, s9
	s_ashr_i32 s49, s48, 31
	s_lshl_b64 s[42:43], s[48:49], 1
	v_and_b32_e32 v21, 63, v123
	global_load_dword v18, v32, s[12:13]
	global_load_dword v16, v85, s[68:69]
	global_load_dword v22, v32, s[10:11]
	global_load_dword v20, v101, s[68:69]
	s_add_u32 s8, s8, s42
	s_addc_u32 s9, s9, s43
	v_lshlrev_b32_e32 v24, 4, v21
	global_load_dwordx4 v[12:15], v24, s[8:9]
	v_lshlrev_b32_e32 v19, 3, v21
	s_add_i32 s49, s73, -1
	v_mov_b32_e32 v25, v32
	v_and_b32_e32 v0, s49, v19
	v_lshl_add_u64 v[42:43], s[8:9], 0, v[24:25]
	v_cmp_ne_u32_e64 s[8:9], 0, v0
	v_mov_b32_e32 v40, v32
	s_and_saveexec_b64 s[10:11], s[8:9]
	s_cbranch_execz .LBB0_507
	global_load_ushort v40, v[42:43], off offset:-2
.LBB0_507:
	s_or_b64 exec, exec, s[10:11]
	s_add_i32 s24, s73, -8
	v_cmp_ne_u32_e64 s[10:11], s24, v0
	v_mov_b32_e32 v34, 0
	v_mov_b32_e32 v39, 0
	s_and_saveexec_b64 s[12:13], s[10:11]
	s_cbranch_execz .LBB0_509
	global_load_ushort v39, v[42:43], off offset:16
.LBB0_509:
	s_or_b64 exec, exec, s[12:13]
	global_load_dwordx4 v[8:11], v[42:43], off offset:1024
	v_bitop3_b32 v0, v19, s49, v103 bitop3:0xc8
	v_cmp_ne_u32_e64 s[12:13], 0, v0
	s_and_saveexec_b64 s[14:15], s[12:13]
	s_cbranch_execz .LBB0_511
	global_load_ushort v34, v[42:43], off offset:1022
.LBB0_511:
	s_or_b64 exec, exec, s[14:15]
	v_cmp_ne_u32_e64 s[14:15], s24, v0
	v_mov_b32_e32 v28, 0
	v_mov_b32_e32 v37, 0
	s_and_saveexec_b64 s[16:17], s[14:15]
	s_cbranch_execz .LBB0_513
	global_load_ushort v37, v[42:43], off offset:1040
.LBB0_513:
	s_or_b64 exec, exec, s[16:17]
	global_load_dwordx4 v[4:7], v[42:43], off offset:2048
	v_bitop3_b32 v0, v19, s49, v118 bitop3:0xc8
	v_cmp_ne_u32_e64 s[16:17], 0, v0
	s_and_saveexec_b64 s[18:19], s[16:17]
	s_cbranch_execz .LBB0_515
	global_load_ushort v28, v[42:43], off offset:2046
.LBB0_515:
	s_or_b64 exec, exec, s[18:19]
	v_cmp_ne_u32_e64 s[18:19], s24, v0
	v_mov_b32_e32 v26, 0
	v_mov_b32_e32 v31, 0
	s_and_saveexec_b64 s[20:21], s[18:19]
	s_cbranch_execz .LBB0_517
	global_load_ushort v31, v[42:43], off offset:2064
.LBB0_517:
	s_or_b64 exec, exec, s[20:21]
	global_load_dwordx4 v[0:3], v[42:43], off offset:3072
	v_bitop3_b32 v17, v19, s49, v119 bitop3:0xc8
	v_cmp_ne_u32_e64 s[20:21], 0, v17
	s_and_saveexec_b64 s[22:23], s[20:21]
	s_cbranch_execz .LBB0_519
	global_load_ushort v26, v[42:43], off offset:3070

.LBB0_521:
	s_or_b64 exec, exec, s[24:25]
	s_waitcnt vmcnt(0)
	v_lshlrev_b32_e32 v40, 16, v40
	v_lshlrev_b32_e32 v39, 16, v39
	v_lshlrev_b32_e32 v34, 16, v34
	v_lshlrev_b32_e32 v37, 16, v37
	v_lshlrev_b32_e32 v28, 16, v28
	v_lshlrev_b32_e32 v31, 16, v31
	v_lshlrev_b32_e32 v26, 16, v26
	v_lshlrev_b32_e32 v17, 16, v17
	v_or_b32_e32 v23, 0x200, v19
	s_waitcnt vmcnt(3)
	v_lshlrev_b32_e32 v41, 16, v12
	v_and_b32_e32 v12, 0xffff0000, v12
	v_pk_fma_f32 v[48:49], v[18:19], v[40:41], v[22:23] op_sel_hi:[0,1,0]
	v_mov_b32_e32 v40, v41
	v_mov_b32_e32 v41, v12
	v_and_b32_e32 v47, 16, v14
	v_and_b32_e32 v46, 0xffff0000, v13
	v_lshlrev_b32_e32 v13, 16, v13
	v_pk_fma_f32 v[40:41], v[16:17], v[40:41], v[48:49] op_sel_hi:[0,1,1]
	v_lshlrev_b32_e32 v44, 16, v15
	v_pk_fma_f32 v[40:41], v[20:21], v[12:13], v[40:41] op_sel_hi:[0,1,1]
	v_pk_fma_f32 v[48:49], v[18:19], v[12:13], v[22:23] op_sel_hi:[0,1,0]
	v_pk_mov_b32 v[12:13], v[12:13], v[46:47] op_sel:[1,0]
	v_and_b32_e32 v42, 0xffff0000, v14
	v_and_b32_e32 v45, 0xffff0000, v15
	v_mov_b32_e32 v43, v44
	v_lshlrev_b32_e32 v15, 16, v14
	v_mov_b32_e32 v14, v46
	v_pk_fma_f32 v[12:13], v[16:17], v[12:13], v[48:49] op_sel_hi:[0,1,1]
	s_mulk_i32 s83, 0x4980
	v_pk_fma_f32 v[46:47], v[20:21], v[14:15], v[12:13] op_sel_hi:[0,1,1]
	v_pk_fma_f32 v[12:13], v[18:19], v[14:15], v[22:23] op_sel_hi:[0,1,0]
	v_pk_mov_b32 v[14:15], v[14:15], v[42:43] op_sel:[1,0]
	s_add_i32 s80, s83, 0
	v_pk_fma_f32 v[12:13], v[16:17], v[14:15], v[12:13] op_sel_hi:[0,1,1]
	v_pk_fma_f32 v[14:15], v[20:21], v[42:43], v[12:13] op_sel_hi:[0,1,1]
	v_pk_fma_f32 v[12:13], v[18:19], v[42:43], v[22:23] op_sel_hi:[0,1,0]
	v_lshrrev_b32_e32 v27, 2, v21
	s_and_b64 s[24:25], s[40:41], exec
	v_and_b32_e32 v50, 24, v19
	v_pk_fma_f32 v[12:13], v[16:17], v[44:45], v[12:13] op_sel_hi:[0,1,1]
	v_mov_b32_e32 v38, v45
	v_mul_u32_u24_e32 v27, 40, v27
	s_waitcnt vmcnt(2)
	v_lshlrev_b32_e32 v35, 16, v8
	v_and_b32_e32 v8, 0xffff0000, v8
	s_cselect_b32 s24, s78, 0xfd9a000
	v_pk_fma_f32 v[38:39], v[20:21], v[38:39], v[12:13] op_sel_hi:[0,1,1]
	v_cvt_pk_bf16_f32 v12, v40, v41
	v_add_lshl_u32 v124, v27, v50, 1
	v_pk_fma_f32 v[40:41], v[18:19], v[34:35], v[22:23] op_sel_hi:[0,1,0]
	v_mov_b32_e32 v34, v35
	v_mov_b32_e32 v35, v8
	s_add_u32 s72, s50, s24
	v_cvt_pk_bf16_f32 v13, v46, v47
	v_cvt_pk_bf16_f32 v14, v14, v15
	v_cvt_pk_bf16_f32 v15, v38, v39
	v_add_u32_e32 v27, s80, v124
	v_and_b32_e32 v39, 16, v10
	v_and_b32_e32 v38, 0xffff0000, v9
	v_lshlrev_b32_e32 v9, 16, v9
	v_pk_fma_f32 v[34:35], v[16:17], v[34:35], v[40:41] op_sel_hi:[0,1,1]
	s_addc_u32 s75, s51, 0
	ds_write_b128 v27, v[12:15] offset:8576
	v_lshlrev_b32_e32 v14, 16, v11
	v_pk_fma_f32 v[34:35], v[20:21], v[8:9], v[34:35] op_sel_hi:[0,1,1]
	v_pk_fma_f32 v[40:41], v[18:19], v[8:9], v[22:23] op_sel_hi:[0,1,0]
	v_pk_mov_b32 v[8:9], v[8:9], v[38:39] op_sel:[1,0]
	s_and_b64 s[24:25], s[40:41], exec
	v_and_b32_e32 v12, 0xffff0000, v10
	v_and_b32_e32 v15, 0xffff0000, v11
	v_mov_b32_e32 v13, v14
	v_lshlrev_b32_e32 v11, 16, v10
	v_mov_b32_e32 v10, v38
	v_pk_fma_f32 v[8:9], v[16:17], v[8:9], v[40:41] op_sel_hi:[0,1,1]
	s_cselect_b32 s74, 11, 8
	v_pk_fma_f32 v[38:39], v[20:21], v[10:11], v[8:9] op_sel_hi:[0,1,1]
	v_pk_fma_f32 v[8:9], v[18:19], v[10:11], v[22:23] op_sel_hi:[0,1,0]
	v_pk_mov_b32 v[10:11], v[10:11], v[12:13] op_sel:[1,0]
	s_lshl_b64 s[24:25], s[66:67], s74
	v_pk_fma_f32 v[8:9], v[16:17], v[10:11], v[8:9] op_sel_hi:[0,1,1]
	s_lshl_b64 s[24:25], s[24:25], 2
	v_pk_fma_f32 v[10:11], v[20:21], v[12:13], v[8:9] op_sel_hi:[0,1,1]
	v_pk_fma_f32 v[8:9], v[18:19], v[12:13], v[22:23] op_sel_hi:[0,1,0]
	s_add_u32 s44, s72, s24
	v_pk_fma_f32 v[8:9], v[16:17], v[14:15], v[8:9] op_sel_hi:[0,1,1]
	v_mov_b32_e32 v36, v15
	s_addc_u32 s45, s75, s25
	v_pk_fma_f32 v[12:13], v[20:21], v[36:37], v[8:9] op_sel_hi:[0,1,1]
	v_cvt_pk_bf16_f32 v9, v38, v39
	global_load_dwordx4 v[36:39], v24, s[44:45]
	v_cvt_pk_bf16_f32 v10, v10, v11
	v_cvt_pk_bf16_f32 v11, v12, v13
	v_lshrrev_b32_e32 v12, 5, v23
	v_mul_u32_u24_e32 v12, 40, v12
	v_add_lshl_u32 v125, v12, v50, 1
	s_waitcnt vmcnt(2)
	v_lshlrev_b32_e32 v29, 16, v4
	v_and_b32_e32 v4, 0xffff0000, v4
	v_cvt_pk_bf16_f32 v8, v34, v35
	v_add_u32_e32 v12, s80, v125
	v_pk_fma_f32 v[14:15], v[18:19], v[28:29], v[22:23] op_sel_hi:[0,1,0]
	v_mov_b32_e32 v28, v29
	v_mov_b32_e32 v29, v4
	ds_write_b128 v12, v[8:11] offset:8576
	v_and_b32_e32 v13, 16, v6
	v_and_b32_e32 v12, 0xffff0000, v5
	v_lshlrev_b32_e32 v5, 16, v5
	v_pk_fma_f32 v[14:15], v[16:17], v[28:29], v[14:15] op_sel_hi:[0,1,1]
	v_lshlrev_b32_e32 v10, 16, v7
	v_pk_fma_f32 v[14:15], v[20:21], v[4:5], v[14:15] op_sel_hi:[0,1,1]
	v_pk_fma_f32 v[28:29], v[18:19], v[4:5], v[22:23] op_sel_hi:[0,1,0]
	v_pk_mov_b32 v[4:5], v[4:5], v[12:13] op_sel:[1,0]
	v_and_b32_e32 v8, 0xffff0000, v6
	v_and_b32_e32 v11, 0xffff0000, v7
	v_mov_b32_e32 v9, v10
	v_lshlrev_b32_e32 v7, 16, v6
	v_mov_b32_e32 v6, v12
	v_pk_fma_f32 v[4:5], v[16:17], v[4:5], v[28:29] op_sel_hi:[0,1,1]
	v_pk_fma_f32 v[12:13], v[20:21], v[6:7], v[4:5] op_sel_hi:[0,1,1]
	v_pk_fma_f32 v[4:5], v[18:19], v[6:7], v[22:23] op_sel_hi:[0,1,0]
	v_pk_mov_b32 v[6:7], v[6:7], v[8:9] op_sel:[1,0]
	v_mov_b32_e32 v30, v11
	v_pk_fma_f32 v[4:5], v[16:17], v[6:7], v[4:5] op_sel_hi:[0,1,1]
	v_pk_fma_f32 v[6:7], v[20:21], v[8:9], v[4:5] op_sel_hi:[0,1,1]
	v_pk_fma_f32 v[4:5], v[18:19], v[8:9], v[22:23] op_sel_hi:[0,1,0]
	v_pk_fma_f32 v[4:5], v[16:17], v[10:11], v[4:5] op_sel_hi:[0,1,1]
	v_or_b32_e32 v25, 0x400, v19
	v_pk_fma_f32 v[8:9], v[20:21], v[30:31], v[4:5] op_sel_hi:[0,1,1]
	v_cvt_pk_bf16_f32 v6, v6, v7
	v_cvt_pk_bf16_f32 v7, v8, v9
	v_lshrrev_b32_e32 v8, 5, v25
	v_mul_u32_u24_e32 v8, 40, v8
	v_add_lshl_u32 v126, v8, v50, 1
	s_waitcnt vmcnt(1)
	v_lshlrev_b32_e32 v27, 16, v0
	v_and_b32_e32 v0, 0xffff0000, v0
	v_cvt_pk_bf16_f32 v4, v14, v15
	v_cvt_pk_bf16_f32 v5, v12, v13
	v_add_u32_e32 v8, s80, v126
	v_pk_fma_f32 v[10:11], v[18:19], v[26:27], v[22:23] op_sel_hi:[0,1,0]
	v_mov_b32_e32 v12, v27
	v_mov_b32_e32 v13, v0
	ds_write_b128 v8, v[4:7] offset:8576
	v_and_b32_e32 v9, 16, v2
	v_and_b32_e32 v8, 0xffff0000, v1
	v_lshlrev_b32_e32 v1, 16, v1
	v_pk_fma_f32 v[10:11], v[16:17], v[12:13], v[10:11] op_sel_hi:[0,1,1]
	v_lshlrev_b32_e32 v6, 16, v3
	v_pk_fma_f32 v[10:11], v[20:21], v[0:1], v[10:11] op_sel_hi:[0,1,1]
	v_pk_fma_f32 v[12:13], v[18:19], v[0:1], v[22:23] op_sel_hi:[0,1,0]
	v_pk_mov_b32 v[0:1], v[0:1], v[8:9] op_sel:[1,0]
	v_and_b32_e32 v4, 0xffff0000, v2
	v_and_b32_e32 v7, 0xffff0000, v3
	v_mov_b32_e32 v5, v6
	v_lshlrev_b32_e32 v3, 16, v2
	v_mov_b32_e32 v2, v8
	v_pk_fma_f32 v[0:1], v[16:17], v[0:1], v[12:13] op_sel_hi:[0,1,1]
	v_pk_fma_f32 v[8:9], v[20:21], v[2:3], v[0:1] op_sel_hi:[0,1,1]
	v_pk_fma_f32 v[0:1], v[18:19], v[2:3], v[22:23] op_sel_hi:[0,1,0]
	v_pk_mov_b32 v[2:3], v[2:3], v[4:5] op_sel:[1,0]
	v_or_b32_e32 v33, 0x600, v19
	v_pk_fma_f32 v[0:1], v[16:17], v[2:3], v[0:1] op_sel_hi:[0,1,1]
	v_pk_fma_f32 v[2:3], v[20:21], v[4:5], v[0:1] op_sel_hi:[0,1,1]
	v_pk_fma_f32 v[0:1], v[18:19], v[4:5], v[22:23] op_sel_hi:[0,1,0]
	v_pk_fma_f32 v[0:1], v[16:17], v[6:7], v[0:1] op_sel_hi:[0,1,1]
	v_mov_b32_e32 v16, v7
	v_pk_fma_f32 v[4:5], v[20:21], v[16:17], v[0:1] op_sel_hi:[0,1,1]
	v_cvt_pk_bf16_f32 v2, v2, v3
	v_cvt_pk_bf16_f32 v3, v4, v5
	v_lshrrev_b32_e32 v4, 5, v33
	v_mul_u32_u24_e32 v4, 40, v4
	v_add_lshl_u32 v127, v4, v50, 1
	v_cvt_pk_bf16_f32 v0, v10, v11
	v_cvt_pk_bf16_f32 v1, v8, v9
	v_add_u32_e32 v4, s80, v127
	ds_write_b128 v4, v[0:3] offset:8576
	v_lshlrev_b32_e32 v3, 2, v21
	v_mov_b32_e32 v34, v32
	v_mov_b32_e32 v35, v32
	v_mov_b32_e32 v25, v32
	v_or_b32_e32 v2, 0x100, v3
	v_mov_b32_e32 v33, v32
	v_mov_b64_e32 v[42:43], v[34:35]
	v_lshl_add_u64 v[0:1], s[44:45], 0, v[24:25]
	v_cmp_gt_u32_e64 s[24:25], s73, v2
	v_mov_b64_e32 v[40:41], v[32:33]
	s_and_saveexec_b64 s[26:27], s[24:25]
	s_cbranch_execz .LBB0_523
	global_load_dwordx4 v[40:43], v[0:1], off offset:1024

.LBB0_572:
	s_xor_b64 s[70:71], s[74:75], -1
	s_add_i32 s74, s72, s66
	s_ashr_i32 s73, s72, 31
	s_ashr_i32 s75, s74, 31
	s_lshl_b64 s[72:73], s[72:73], 2
	s_add_u32 s72, s68, s72
	s_addc_u32 s73, s69, s73
	s_lshl_b64 s[86:87], s[74:75], 2
	s_add_u32 s90, s54, s86
	s_addc_u32 s91, s55, s87
	s_add_u32 s86, s64, s86
	global_load_dword v98, v120, s[72:73]
	global_load_dword v34, v121, s[72:73]
	s_addc_u32 s87, s65, s87
	global_load_dword v100, v32, s[72:73]
	global_load_dword v102, v32, s[90:91]
	global_load_dword v106, v32, s[86:87]
	v_mad_i64_i32 v[0:1], s[72:73], s74, v122, v[96:97]
	global_load_dwordx4 v[80:83], v[0:1], off
	v_mov_b32_e32 v115, 0
	v_mov_b32_e32 v116, 0
	s_and_saveexec_b64 s[72:73], s[8:9]
	s_cbranch_execz .LBB0_574
	global_load_ushort v116, v[0:1], off offset:-2
.LBB0_574:
	s_or_b64 exec, exec, s[72:73]
	s_and_saveexec_b64 s[72:73], s[10:11]
	s_cbranch_execz .LBB0_576
	global_load_ushort v115, v[0:1], off offset:16
.LBB0_576:
	s_or_b64 exec, exec, s[72:73]
	global_load_dwordx4 v[76:79], v[0:1], off offset:1024
	v_mov_b32_e32 v111, 0
	v_mov_b32_e32 v112, 0
	s_and_saveexec_b64 s[72:73], s[12:13]
	s_cbranch_execz .LBB0_578
	global_load_ushort v112, v[0:1], off offset:1022
.LBB0_578:
	s_or_b64 exec, exec, s[72:73]
	s_and_saveexec_b64 s[72:73], s[14:15]
	s_cbranch_execz .LBB0_580
	global_load_ushort v111, v[0:1], off offset:1040
.LBB0_580:
	s_or_b64 exec, exec, s[72:73]
	global_load_dwordx4 v[72:75], v[0:1], off offset:2048
	v_mov_b32_e32 v107, 0
	v_mov_b32_e32 v108, 0
	s_and_saveexec_b64 s[72:73], s[16:17]
	s_cbranch_execz .LBB0_582
	global_load_ushort v108, v[0:1], off offset:2046
.LBB0_582:
	s_or_b64 exec, exec, s[72:73]
	s_and_saveexec_b64 s[72:73], s[18:19]
	s_cbranch_execz .LBB0_584
	global_load_ushort v107, v[0:1], off offset:2064
.LBB0_584:
	s_or_b64 exec, exec, s[72:73]
	global_load_dwordx4 v[68:71], v[0:1], off offset:3072
	v_mov_b32_e32 v99, 0
	v_mov_b32_e32 v104, 0
	s_and_saveexec_b64 s[72:73], s[20:21]
	s_cbranch_execz .LBB0_586
	global_load_ushort v104, v[0:1], off offset:3070
.LBB0_586:
	s_or_b64 exec, exec, s[72:73]
	s_and_saveexec_b64 s[72:73], s[22:23]
	s_cbranch_execz .LBB0_588
	global_load_ushort v99, v[0:1], off offset:3088

.LBB0_589:
	v_add_u32_e32 v113, v105, v131
	v_add_u32_e32 v117, v35, v131
	v_cmp_gt_u32_e32 vcc, s82, v109
	v_add_u32_e32 v114, v33, v131
	ds_read2_b32 v[210:211], v113 offset1:1
	ds_read2_b32 v[212:213], v113 offset0:2 offset1:3
	ds_read2_b32 v[214:215], v113 offset0:8 offset1:9
	ds_read2_b32 v[216:217], v113 offset0:10 offset1:11
	v_cndmask_b32_e32 v113, v132, v117, vcc
	v_cmp_gt_u32_e32 vcc, s82, v110
	s_nop 1
	v_cndmask_b32_e32 v114, v132, v114, vcc
	ds_read_b128 v[218:221], v113
	ds_read_b128 v[222:225], v113 offset:32
	ds_read_b128 v[226:229], v114
	ds_read_b128 v[230:233], v114 offset:32
	s_waitcnt lgkmcnt(3)
	v_mfma_f32_32x32x16_bf16 v[16:31], v[210:213], v[218:221], v[16:31]
	s_add_i32 s72, s72, -1
	v_add_u32_e32 v109, -1, v109
	v_add_u32_e32 v110, -1, v110
	v_subrev_u32_e32 v105, 64, v105
	v_add_u32_e32 v33, 0xffffffb0, v33
	v_add_u32_e32 v35, 0xffffffb0, v35
	s_cmp_eq_u32 s72, 0
	s_waitcnt lgkmcnt(1)
	v_mfma_f32_32x32x16_bf16 v[0:15], v[210:213], v[226:229], v[0:15]
	v_mfma_f32_32x32x16_bf16 v[16:31], v[214:217], v[222:225], v[16:31]
	s_waitcnt lgkmcnt(0)
	v_mfma_f32_32x32x16_bf16 v[0:15], v[214:217], v[230:233], v[0:15]
	s_cbranch_scc0 .LBB0_589
	s_waitcnt vmcnt(0)
	v_lshlrev_b32_e32 v116, 16, v116
	v_lshlrev_b32_e32 v115, 16, v115
	v_lshlrev_b32_e32 v112, 16, v112
	v_lshlrev_b32_e32 v111, 16, v111
	v_lshlrev_b32_e32 v108, 16, v108
	v_lshlrev_b32_e32 v107, 16, v107
	v_lshlrev_b32_e32 v104, 16, v104
	v_lshlrev_b32_e32 v99, 16, v99
	s_add_i32 s73, s80, s85
	v_add_u32_e32 v33, s73, v205
	ds_read_b64 v[210:211], v33
	s_add_i32 s72, s80, s84
	v_add_u32_e32 v35, s72, v205
	s_waitcnt vmcnt(3)
	v_lshlrev_b32_e32 v117, 16, v80
	s_waitcnt vmcnt(2)
	v_lshlrev_b32_e32 v113, 16, v76
	s_waitcnt lgkmcnt(0)
	v_lshlrev_b32_e32 v212, 16, v210
	v_and_b32_e32 v213, 0xffff0000, v210
	v_lshlrev_b32_e32 v210, 16, v211
	v_and_b32_e32 v211, 0xffff0000, v211
	v_pk_fma_f32 v[16:17], v[106:107], v[212:213], v[16:17] op_sel_hi:[0,1,1]
	v_pk_fma_f32 v[18:19], v[106:107], v[210:211], v[18:19] op_sel_hi:[0,1,1]
	v_cvt_pk_bf16_f32 v16, v16, v17
	v_cvt_pk_bf16_f32 v17, v18, v19
	ds_write_b64 v35, v[16:17]
	ds_read_b64 v[16:17], v33 offset:16
	s_waitcnt vmcnt(1)
	v_lshlrev_b32_e32 v109, 16, v72
	s_waitcnt vmcnt(0)
	v_lshlrev_b32_e32 v105, 16, v68
	s_mov_b64 s[74:75], 0
	s_and_b64 vcc, exec, s[70:71]
	s_waitcnt lgkmcnt(0)
	v_lshlrev_b32_e32 v18, 16, v16
	v_and_b32_e32 v19, 0xffff0000, v16
	v_pk_fma_f32 v[18:19], v[106:107], v[18:19], v[20:21] op_sel_hi:[0,1,1]
	v_cvt_pk_bf16_f32 v16, v18, v19
	v_lshlrev_b32_e32 v18, 16, v17
	v_and_b32_e32 v19, 0xffff0000, v17
	v_pk_fma_f32 v[18:19], v[106:107], v[18:19], v[22:23] op_sel_hi:[0,1,1]
	v_cvt_pk_bf16_f32 v17, v18, v19
	ds_write_b64 v35, v[16:17] offset:16
	ds_read_b64 v[16:17], v33 offset:32
	v_add_u32_e32 v20, s73, v206
	v_add_u32_e32 v22, s72, v124
	s_waitcnt lgkmcnt(0)
	v_lshlrev_b32_e32 v18, 16, v16
	v_and_b32_e32 v19, 0xffff0000, v16
	v_pk_fma_f32 v[18:19], v[106:107], v[18:19], v[24:25] op_sel_hi:[0,1,1]
	v_cvt_pk_bf16_f32 v16, v18, v19
	v_lshlrev_b32_e32 v18, 16, v17
	v_and_b32_e32 v19, 0xffff0000, v17
	v_pk_fma_f32 v[18:19], v[106:107], v[18:19], v[26:27] op_sel_hi:[0,1,1]
	v_cvt_pk_bf16_f32 v17, v18, v19
	ds_write_b64 v35, v[16:17] offset:32
	ds_read_b64 v[16:17], v33 offset:48
	s_waitcnt lgkmcnt(0)
	v_lshlrev_b32_e32 v18, 16, v16
	v_and_b32_e32 v19, 0xffff0000, v16
	v_pk_fma_f32 v[18:19], v[106:107], v[18:19], v[28:29] op_sel_hi:[0,1,1]
	v_cvt_pk_bf16_f32 v16, v18, v19
	v_lshlrev_b32_e32 v18, 16, v17
	v_and_b32_e32 v19, 0xffff0000, v17
	v_pk_fma_f32 v[18:19], v[106:107], v[18:19], v[30:31] op_sel_hi:[0,1,1]
	v_cvt_pk_bf16_f32 v17, v18, v19
	ds_write_b64 v35, v[16:17] offset:48
	ds_read_b64 v[16:17], v20
	s_waitcnt lgkmcnt(0)
	v_lshlrev_b32_e32 v18, 16, v16
	v_and_b32_e32 v19, 0xffff0000, v16
	v_lshlrev_b32_e32 v16, 16, v17
	v_and_b32_e32 v17, 0xffff0000, v17
	v_pk_fma_f32 v[0:1], v[106:107], v[18:19], v[0:1] op_sel_hi:[0,1,1]
	v_pk_fma_f32 v[2:3], v[106:107], v[16:17], v[2:3] op_sel_hi:[0,1,1]
	v_cvt_pk_bf16_f32 v0, v0, v1
	v_cvt_pk_bf16_f32 v1, v2, v3
	v_add_u32_e32 v16, s72, v206
	ds_write_b64 v16, v[0:1]
	ds_read_b64 v[0:1], v20 offset:16
	s_waitcnt lgkmcnt(0)
	v_lshlrev_b32_e32 v2, 16, v0
	v_and_b32_e32 v3, 0xffff0000, v0
	v_pk_fma_f32 v[2:3], v[106:107], v[2:3], v[4:5] op_sel_hi:[0,1,1]
	v_cvt_pk_bf16_f32 v0, v2, v3
	v_lshlrev_b32_e32 v2, 16, v1
	v_and_b32_e32 v3, 0xffff0000, v1
	v_pk_fma_f32 v[2:3], v[106:107], v[2:3], v[6:7] op_sel_hi:[0,1,1]
	v_cvt_pk_bf16_f32 v1, v2, v3
	ds_write_b64 v16, v[0:1] offset:16
	ds_read_b64 v[0:1], v20 offset:32
	v_lshlrev_b32_e32 v6, 16, v83
	v_and_b32_e32 v4, 0xffff0000, v82
	v_mov_b32_e32 v5, v6
	v_and_b32_e32 v7, 0xffff0000, v83
	s_waitcnt lgkmcnt(0)
	v_lshlrev_b32_e32 v2, 16, v0
	v_and_b32_e32 v3, 0xffff0000, v0
	v_pk_fma_f32 v[2:3], v[106:107], v[2:3], v[8:9] op_sel_hi:[0,1,1]
	v_cvt_pk_bf16_f32 v0, v2, v3
	v_lshlrev_b32_e32 v2, 16, v1
	v_and_b32_e32 v3, 0xffff0000, v1
	v_pk_fma_f32 v[2:3], v[106:107], v[2:3], v[10:11] op_sel_hi:[0,1,1]
	v_cvt_pk_bf16_f32 v1, v2, v3
	ds_write_b64 v16, v[0:1] offset:32
	ds_read_b64 v[0:1], v20 offset:48
	v_mov_b32_e32 v20, v117
	v_and_b32_e32 v11, 16, v82
	v_and_b32_e32 v10, 0xffff0000, v81
	v_mov_b32_e32 v114, v7
	s_waitcnt lgkmcnt(0)
	v_lshlrev_b32_e32 v2, 16, v0
	v_and_b32_e32 v3, 0xffff0000, v0
	v_pk_fma_f32 v[2:3], v[106:107], v[2:3], v[12:13] op_sel_hi:[0,1,1]
	v_cvt_pk_bf16_f32 v0, v2, v3
	v_lshlrev_b32_e32 v2, 16, v1
	v_and_b32_e32 v3, 0xffff0000, v1
	v_pk_fma_f32 v[2:3], v[106:107], v[2:3], v[14:15] op_sel_hi:[0,1,1]
	v_cvt_pk_bf16_f32 v1, v2, v3
	ds_write_b64 v16, v[0:1] offset:48
	s_waitcnt lgkmcnt(0)
	ds_read_b128 v[0:3], v22
	v_lshlrev_b32_e32 v13, 16, v82
	v_mov_b32_e32 v12, v10
	s_waitcnt lgkmcnt(0)
	v_lshlrev_b32_e32 v14, 16, v2
	v_and_b32_e32 v15, 0xffff0000, v2
	v_and_b32_e32 v2, 0xffff0000, v80
	v_lshlrev_b32_e32 v16, 16, v1
	v_and_b32_e32 v17, 0xffff0000, v1
	v_lshlrev_b32_e32 v18, 16, v0
	v_and_b32_e32 v19, 0xffff0000, v0
	v_pk_fma_f32 v[0:1], v[100:101], v[116:117], v[102:103] op_sel_hi:[0,1,0]
	v_mov_b32_e32 v21, v2
	v_lshlrev_b32_e32 v8, 16, v3
	v_and_b32_e32 v9, 0xffff0000, v3
	v_lshlrev_b32_e32 v3, 16, v81
	v_pk_fma_f32 v[0:1], v[98:99], v[20:21], v[0:1] op_sel_hi:[0,1,1]
	v_pk_fma_f32 v[0:1], v[34:35], v[2:3], v[0:1] op_sel_hi:[0,1,1]
	v_pk_mul_f32 v[0:1], v[0:1], v[18:19]
	v_pk_fma_f32 v[18:19], v[100:101], v[2:3], v[102:103] op_sel_hi:[0,1,0]
	v_pk_mov_b32 v[2:3], v[2:3], v[10:11] op_sel:[1,0]
	v_pk_fma_f32 v[10:11], v[100:101], v[12:13], v[102:103] op_sel_hi:[0,1,0]
	v_pk_fma_f32 v[2:3], v[98:99], v[2:3], v[18:19] op_sel_hi:[0,1,1]
	v_pk_fma_f32 v[2:3], v[34:35], v[12:13], v[2:3] op_sel_hi:[0,1,1]
	v_pk_mov_b32 v[12:13], v[12:13], v[4:5] op_sel:[1,0]
	v_pk_mul_f32 v[2:3], v[2:3], v[16:17]
	v_pk_fma_f32 v[10:11], v[98:99], v[12:13], v[10:11] op_sel_hi:[0,1,1]
	v_pk_fma_f32 v[10:11], v[34:35], v[4:5], v[10:11] op_sel_hi:[0,1,1]
	v_pk_fma_f32 v[4:5], v[100:101], v[4:5], v[102:103] op_sel_hi:[0,1,0]
	v_pk_fma_f32 v[4:5], v[98:99], v[6:7], v[4:5] op_sel_hi:[0,1,1]
	v_pk_fma_f32 v[4:5], v[34:35], v[114:115], v[4:5] op_sel_hi:[0,1,1]
	v_pk_mul_f32 v[10:11], v[10:11], v[14:15]
	v_pk_mul_f32 v[4:5], v[4:5], v[8:9]
	v_cvt_pk_bf16_f32 v0, v0, v1
	v_cvt_pk_bf16_f32 v1, v2, v3
	v_cvt_pk_bf16_f32 v2, v10, v11
	v_cvt_pk_bf16_f32 v3, v4, v5
	ds_write_b128 v22, v[0:3]
	v_add_u32_e32 v22, s72, v125
	ds_read_b128 v[0:3], v22
	v_mov_b32_e32 v20, v113
	v_and_b32_e32 v11, 16, v78
	v_and_b32_e32 v10, 0xffff0000, v77
	v_lshlrev_b32_e32 v6, 16, v79
	s_waitcnt lgkmcnt(0)
	v_lshlrev_b32_e32 v14, 16, v2
	v_and_b32_e32 v15, 0xffff0000, v2
	v_and_b32_e32 v2, 0xffff0000, v76
	v_lshlrev_b32_e32 v16, 16, v1
	v_and_b32_e32 v17, 0xffff0000, v1
	v_lshlrev_b32_e32 v18, 16, v0
	v_and_b32_e32 v19, 0xffff0000, v0
	v_pk_fma_f32 v[0:1], v[100:101], v[112:113], v[102:103] op_sel_hi:[0,1,0]
	v_mov_b32_e32 v21, v2
	v_lshlrev_b32_e32 v8, 16, v3
	v_and_b32_e32 v9, 0xffff0000, v3
	v_lshlrev_b32_e32 v3, 16, v77
	v_pk_fma_f32 v[0:1], v[98:99], v[20:21], v[0:1] op_sel_hi:[0,1,1]
	v_pk_fma_f32 v[0:1], v[34:35], v[2:3], v[0:1] op_sel_hi:[0,1,1]
	v_pk_mul_f32 v[0:1], v[0:1], v[18:19]
	v_pk_fma_f32 v[18:19], v[100:101], v[2:3], v[102:103] op_sel_hi:[0,1,0]
	v_pk_mov_b32 v[2:3], v[2:3], v[10:11] op_sel:[1,0]
	v_and_b32_e32 v4, 0xffff0000, v78
	v_mov_b32_e32 v5, v6
	v_lshlrev_b32_e32 v13, 16, v78
	v_mov_b32_e32 v12, v10
	v_pk_fma_f32 v[2:3], v[98:99], v[2:3], v[18:19] op_sel_hi:[0,1,1]
	v_pk_fma_f32 v[2:3], v[34:35], v[12:13], v[2:3] op_sel_hi:[0,1,1]
	v_pk_fma_f32 v[10:11], v[100:101], v[12:13], v[102:103] op_sel_hi:[0,1,0]
	v_pk_mov_b32 v[12:13], v[12:13], v[4:5] op_sel:[1,0]
	v_and_b32_e32 v7, 0xffff0000, v79
	v_pk_fma_f32 v[10:11], v[98:99], v[12:13], v[10:11] op_sel_hi:[0,1,1]
	v_pk_fma_f32 v[10:11], v[34:35], v[4:5], v[10:11] op_sel_hi:[0,1,1]
	v_pk_fma_f32 v[4:5], v[100:101], v[4:5], v[102:103] op_sel_hi:[0,1,0]
	v_pk_fma_f32 v[4:5], v[98:99], v[6:7], v[4:5] op_sel_hi:[0,1,1]
	v_mov_b32_e32 v110, v7
	v_pk_fma_f32 v[4:5], v[34:35], v[110:111], v[4:5] op_sel_hi:[0,1,1]
	v_pk_mul_f32 v[2:3], v[2:3], v[16:17]
	v_pk_mul_f32 v[10:11], v[10:11], v[14:15]
	v_pk_mul_f32 v[4:5], v[4:5], v[8:9]
	v_cvt_pk_bf16_f32 v0, v0, v1
	v_cvt_pk_bf16_f32 v1, v2, v3
	v_cvt_pk_bf16_f32 v2, v10, v11
	v_cvt_pk_bf16_f32 v3, v4, v5
	ds_write_b128 v22, v[0:3]
	v_add_u32_e32 v22, s72, v126
	ds_read_b128 v[0:3], v22
	v_mov_b32_e32 v20, v109
	v_and_b32_e32 v11, 16, v74
	v_and_b32_e32 v10, 0xffff0000, v73
	v_lshlrev_b32_e32 v6, 16, v75
	s_waitcnt lgkmcnt(0)
	v_lshlrev_b32_e32 v14, 16, v2
	v_and_b32_e32 v15, 0xffff0000, v2
	v_and_b32_e32 v2, 0xffff0000, v72
	v_lshlrev_b32_e32 v16, 16, v1
	v_and_b32_e32 v17, 0xffff0000, v1
	v_lshlrev_b32_e32 v18, 16, v0
	v_and_b32_e32 v19, 0xffff0000, v0
	v_pk_fma_f32 v[0:1], v[100:101], v[108:109], v[102:103] op_sel_hi:[0,1,0]
	v_mov_b32_e32 v21, v2
	v_lshlrev_b32_e32 v8, 16, v3
	v_and_b32_e32 v9, 0xffff0000, v3
	v_lshlrev_b32_e32 v3, 16, v73
	v_pk_fma_f32 v[0:1], v[98:99], v[20:21], v[0:1] op_sel_hi:[0,1,1]
	v_pk_fma_f32 v[0:1], v[34:35], v[2:3], v[0:1] op_sel_hi:[0,1,1]
	v_pk_mul_f32 v[0:1], v[0:1], v[18:19]
	v_pk_fma_f32 v[18:19], v[100:101], v[2:3], v[102:103] op_sel_hi:[0,1,0]
	v_pk_mov_b32 v[2:3], v[2:3], v[10:11] op_sel:[1,0]
	v_and_b32_e32 v4, 0xffff0000, v74
	v_mov_b32_e32 v5, v6
	v_lshlrev_b32_e32 v13, 16, v74
	v_mov_b32_e32 v12, v10
	v_pk_fma_f32 v[2:3], v[98:99], v[2:3], v[18:19] op_sel_hi:[0,1,1]
	v_pk_fma_f32 v[2:3], v[34:35], v[12:13], v[2:3] op_sel_hi:[0,1,1]
	v_pk_fma_f32 v[10:11], v[100:101], v[12:13], v[102:103] op_sel_hi:[0,1,0]
	v_pk_mov_b32 v[12:13], v[12:13], v[4:5] op_sel:[1,0]
	v_and_b32_e32 v7, 0xffff0000, v75
	v_pk_fma_f32 v[10:11], v[98:99], v[12:13], v[10:11] op_sel_hi:[0,1,1]
	v_pk_fma_f32 v[10:11], v[34:35], v[4:5], v[10:11] op_sel_hi:[0,1,1]
	v_pk_fma_f32 v[4:5], v[100:101], v[4:5], v[102:103] op_sel_hi:[0,1,0]
	v_pk_fma_f32 v[4:5], v[98:99], v[6:7], v[4:5] op_sel_hi:[0,1,1]
	v_mov_b32_e32 v106, v7
	v_pk_fma_f32 v[4:5], v[34:35], v[106:107], v[4:5] op_sel_hi:[0,1,1]
	v_pk_mul_f32 v[2:3], v[2:3], v[16:17]
	v_pk_mul_f32 v[10:11], v[10:11], v[14:15]
	v_pk_mul_f32 v[4:5], v[4:5], v[8:9]
	v_cvt_pk_bf16_f32 v0, v0, v1
	v_cvt_pk_bf16_f32 v1, v2, v3
	v_cvt_pk_bf16_f32 v2, v10, v11
	v_cvt_pk_bf16_f32 v3, v4, v5
	ds_write_b128 v22, v[0:3]
	v_add_u32_e32 v22, s72, v127
	ds_read_b128 v[0:3], v22
	v_mov_b32_e32 v20, v105
	v_and_b32_e32 v11, 16, v70
	v_and_b32_e32 v10, 0xffff0000, v69
	v_lshlrev_b32_e32 v6, 16, v71
	s_waitcnt lgkmcnt(0)
	v_lshlrev_b32_e32 v14, 16, v2
	v_and_b32_e32 v15, 0xffff0000, v2
	v_and_b32_e32 v2, 0xffff0000, v68
	v_lshlrev_b32_e32 v16, 16, v1
	v_and_b32_e32 v17, 0xffff0000, v1
	v_lshlrev_b32_e32 v18, 16, v0
	v_and_b32_e32 v19, 0xffff0000, v0
	v_pk_fma_f32 v[0:1], v[100:101], v[104:105], v[102:103] op_sel_hi:[0,1,0]
	v_mov_b32_e32 v21, v2
	v_lshlrev_b32_e32 v8, 16, v3
	v_and_b32_e32 v9, 0xffff0000, v3
	v_lshlrev_b32_e32 v3, 16, v69
	v_pk_fma_f32 v[0:1], v[98:99], v[20:21], v[0:1] op_sel_hi:[0,1,1]
	v_pk_fma_f32 v[0:1], v[34:35], v[2:3], v[0:1] op_sel_hi:[0,1,1]
	v_pk_mul_f32 v[0:1], v[0:1], v[18:19]
	v_pk_fma_f32 v[18:19], v[100:101], v[2:3], v[102:103] op_sel_hi:[0,1,0]
	v_pk_mov_b32 v[2:3], v[2:3], v[10:11] op_sel:[1,0]
	v_and_b32_e32 v4, 0xffff0000, v70
	v_mov_b32_e32 v5, v6
	v_lshlrev_b32_e32 v13, 16, v70
	v_mov_b32_e32 v12, v10
	v_pk_fma_f32 v[2:3], v[98:99], v[2:3], v[18:19] op_sel_hi:[0,1,1]
	v_pk_fma_f32 v[2:3], v[34:35], v[12:13], v[2:3] op_sel_hi:[0,1,1]
	v_pk_fma_f32 v[10:11], v[100:101], v[12:13], v[102:103] op_sel_hi:[0,1,0]
	v_pk_mov_b32 v[12:13], v[12:13], v[4:5] op_sel:[1,0]
	v_and_b32_e32 v7, 0xffff0000, v71
	v_pk_fma_f32 v[10:11], v[98:99], v[12:13], v[10:11] op_sel_hi:[0,1,1]
	v_pk_fma_f32 v[10:11], v[34:35], v[4:5], v[10:11] op_sel_hi:[0,1,1]
	v_pk_fma_f32 v[4:5], v[100:101], v[4:5], v[102:103] op_sel_hi:[0,1,0]
	v_pk_fma_f32 v[4:5], v[98:99], v[6:7], v[4:5] op_sel_hi:[0,1,1]
	v_mov_b32_e32 v98, v7
	v_pk_fma_f32 v[4:5], v[34:35], v[98:99], v[4:5] op_sel_hi:[0,1,1]
	v_pk_mul_f32 v[2:3], v[2:3], v[16:17]
	v_pk_mul_f32 v[10:11], v[10:11], v[14:15]
	v_pk_mul_f32 v[4:5], v[4:5], v[8:9]
	v_cvt_pk_bf16_f32 v0, v0, v1
	v_cvt_pk_bf16_f32 v1, v2, v3
	v_cvt_pk_bf16_f32 v2, v10, v11
	v_cvt_pk_bf16_f32 v3, v4, v5
	ds_write_b128 v22, v[0:3]
	s_waitcnt lgkmcnt(0)
	s_movk_i32 s72, 0x400
	s_cbranch_vccz .LBB0_536
	v_cmp_gt_i32_e32 vcc, s47, v123
	s_waitcnt lgkmcnt(0)
	s_barrier
	s_and_saveexec_b64 s[8:9], vcc
	s_cbranch_execz .LBB0_504
	s_lshl_b32 s10, s79, 1
	s_add_u32 s10, s76, s10
	s_addc_u32 s11, s77, 0
	s_mov_b64 s[12:13], 0
